# v91 + P6: once-read branch outputs / LSE / gated SSD rows loaded with nt (streaming)
# speedup vs baseline: 1.0073x; 1.0053x over previous
; __device__ __forceinline__ unsigned pk2(float lo, float hi) { f32x2_t v = {lo, hi}; bf16x2_t b = __builtin_convertvector(v, bf16x2_t); return __builtin_bit_cast(unsigned, b); }
; __device__ __forceinline__ float wsum(float v) { v += __shfl_xor(v, 32); v += __shfl_xor(v, 16); v += __shfl_xor(v, 8); v += __shfl_xor(v, 4); v += __shfl_xor(v, 2); v += __shfl_xor(v, 1); return v; }
; __device__ __forceinline__ void rms_half(const bfu* src, const float* gam, bfu* dst, int lane) {
;     float a[8], c[8];
;     ld8f(src + lane * 8, a); ld8f(src + 512 + lane * 8, c);
;     float ss = 0.f;
; #pragma unroll
;     for (int j = 0; j < 8; ++j) ss += a[j] * a[j] + c[j] * c[j];
;     ss = wsum(ss);
;     const float rs = rsqrtf(ss * (1.f / 1024.f) + EPS);
;     float g0[8], g1[8]; ld8f32(gam + lane * 8, g0); ld8f32(gam + 512 + lane * 8, g1);
;     uint4 o0, o1;
;     o0.x = pk2(a[0] * rs * g0[0], a[1] * rs * g0[1]); o0.y = pk2(a[2] * rs * g0[2], a[3] * rs * g0[3]); o0.z = pk2(a[4] * rs * g0[4], a[5] * rs * g0[5]); o0.w = pk2(a[6] * rs * g0[6], a[7] * rs * g0[7]);
;     o1.x = pk2(c[0] * rs * g1[0], c[1] * rs * g1[1]); o1.y = pk2(c[2] * rs * g1[2], c[3] * rs * g1[3]); o1.z = pk2(c[4] * rs * g1[4], c[5] * rs * g1[5]); o1.w = pk2(c[6] * rs * g1[6], c[7] * rs * g1[7]);
;     *(uint4*)(dst + lane * 8) = o0; *(uint4*)(dst + 512 + lane * 8) = o1;
; }
; __device__ __forceinline__ void phase6(const Params& p, int bid, int G) {
;     ...
;         if (row < MP) attn_merge_rms(p, row, mix + (size_t)row * 2048, lane);
;         else rms_half(att + (size_t)row * 1024, p.attn_g, mix + (size_t)row * 2048, lane);
;         rms_half(yg + (size_t)row * 1024, p.ssm_g, mix + (size_t)row * 2048 + 1024, lane);
.LBB0_603:
	s_or_b64 exec, exec, s[18:19]
	v_lshlrev_b64 v[38:39], 12, v[38:39]
	v_cvt_pk_bf16_f32 v29, v28, v29
	v_cvt_pk_bf16_f32 v28, v26, v27
	v_cvt_pk_bf16_f32 v27, v24, v25
	v_cvt_pk_bf16_f32 v26, v22, v23
	v_lshl_add_u64 v[52:53], v[8:9], 0, v[38:39]
	v_cvt_pk_bf16_f32 v36, v36, v37
	v_cvt_pk_bf16_f32 v35, v34, v35
	v_cvt_pk_bf16_f32 v34, v32, v33
	v_cvt_pk_bf16_f32 v37, v30, v31
	global_store_dwordx4 v[52:53], v[26:29], off
	global_store_dwordx4 v[52:53], v[34:37], off offset:1024
	v_lshl_add_u64 v[54:55], v[10:11], 0, v[20:21]
	global_load_dwordx4 v[20:23], v[54:55], off nt
	global_load_dwordx4 v[24:27], v[54:55], off offset:1024 nt
	v_lshl_add_u64 v[18:19], v[18:19], 0, s[10:11]
	v_cmp_lt_i32_e64 s[8:9], s24, v18
	v_lshl_add_u64 v[14:15], v[14:15], 0, s[12:13]
	v_lshl_add_u64 v[12:13], v[12:13], 0, s[12:13]
	s_or_b64 s[16:17], s[8:9], s[16:17]
	v_lshl_add_u64 v[16:17], v[16:17], 0, s[14:15]
	s_waitcnt vmcnt(1)
	v_lshlrev_b32_e32 v54, 16, v20
	s_waitcnt vmcnt(0)
	v_lshlrev_b32_e32 v58, 16, v24
	v_and_b32_e32 v59, 0xffff0000, v24
	v_and_b32_e32 v55, 0xffff0000, v20
	v_lshlrev_b32_e32 v24, 16, v25
	v_and_b32_e32 v25, 0xffff0000, v25
	v_pk_mul_f32 v[64:65], v[58:59], v[58:59]
	v_lshlrev_b32_e32 v20, 16, v21
	v_and_b32_e32 v21, 0xffff0000, v21
	v_pk_mul_f32 v[62:63], v[24:25], v[24:25]
	v_pk_fma_f32 v[64:65], v[54:55], v[54:55], v[64:65]
	v_lshlrev_b32_e32 v60, 16, v26
	v_and_b32_e32 v61, 0xffff0000, v26
	v_pk_fma_f32 v[62:63], v[20:21], v[20:21], v[62:63]
	v_add_f32_e32 v0, v64, v65
	v_lshlrev_b32_e32 v56, 16, v22
	v_and_b32_e32 v57, 0xffff0000, v22
	v_pk_mul_f32 v[68:69], v[60:61], v[60:61]
	v_add_f32_e32 v0, v0, v62
	v_lshlrev_b32_e32 v26, 16, v27
	v_and_b32_e32 v27, 0xffff0000, v27
	v_pk_fma_f32 v[68:69], v[56:57], v[56:57], v[68:69]
	v_add_f32_e32 v0, v63, v0
	v_lshlrev_b32_e32 v22, 16, v23
	v_and_b32_e32 v23, 0xffff0000, v23
	v_pk_mul_f32 v[66:67], v[26:27], v[26:27]
	v_add_f32_e32 v0, v68, v0
	v_pk_fma_f32 v[66:67], v[22:23], v[22:23], v[66:67]
	v_add_f32_e32 v0, v69, v0
	v_add_f32_e32 v0, v66, v0
	v_add_f32_e32 v0, v67, v0
	ds_bpermute_b32 v47, v40, v0
	s_waitcnt lgkmcnt(0)
	v_add_f32_e32 v0, v0, v47
	ds_bpermute_b32 v47, v41, v0
	s_waitcnt lgkmcnt(0)
	v_add_f32_e32 v0, v0, v47
	ds_bpermute_b32 v47, v42, v0
	s_waitcnt lgkmcnt(0)
	v_add_f32_e32 v0, v0, v47
	ds_bpermute_b32 v47, v43, v0
	s_waitcnt lgkmcnt(0)
	v_add_f32_e32 v0, v0, v47
	ds_bpermute_b32 v47, v44, v0
	s_waitcnt lgkmcnt(0)
	v_add_f32_e32 v0, v0, v47
	ds_bpermute_b32 v47, v45, v0
	s_waitcnt lgkmcnt(0)
	v_add_f32_e32 v0, v0, v47
	v_fmamk_f32 v0, v0, 0x3a800000, v46
	v_mul_f32_e32 v47, 0x4b800000, v0
	v_cmp_gt_f32_e32 vcc, s20, v0
	s_nop 1
	v_cndmask_b32_e32 v0, v0, v47, vcc
	v_rsq_f32_e32 v0, v0
	s_nop 0
	v_mul_f32_e32 v47, 0x45800000, v0
	v_cndmask_b32_e32 v0, v0, v47, vcc
	v_pk_mul_f32 v[54:55], v[0:1], v[54:55] op_sel_hi:[0,1]
	v_pk_mul_f32 v[20:21], v[0:1], v[20:21] op_sel_hi:[0,1]
	v_pk_mul_f32 v[56:57], v[0:1], v[56:57] op_sel_hi:[0,1]
	v_pk_mul_f32 v[22:23], v[0:1], v[22:23] op_sel_hi:[0,1]
	v_pk_mul_f32 v[58:59], v[0:1], v[58:59] op_sel_hi:[0,1]
	v_pk_mul_f32 v[24:25], v[0:1], v[24:25] op_sel_hi:[0,1]
	v_pk_mul_f32 v[60:61], v[0:1], v[60:61] op_sel_hi:[0,1]
	v_pk_mul_f32 v[26:27], v[0:1], v[26:27] op_sel_hi:[0,1]
	s_waitcnt vmcnt(0)
	v_mov_b64_e32 v[28:29], v[130:131]
	v_mov_b64_e32 v[30:31], v[132:133]
	v_mov_b64_e32 v[32:33], v[134:135]
	v_mov_b64_e32 v[34:35], v[136:137]
	v_mov_b64_e32 v[36:37], v[138:139]
	v_mov_b64_e32 v[38:39], v[140:141]
	v_mov_b64_e32 v[48:49], v[142:143]
	v_mov_b64_e32 v[50:51], v[144:145]
	v_pk_mul_f32 v[48:49], v[48:49], v[54:55]
	v_pk_mul_f32 v[50:51], v[50:51], v[20:21]
	v_pk_mul_f32 v[36:37], v[36:37], v[56:57]
	v_pk_mul_f32 v[38:39], v[38:39], v[22:23]
	v_pk_mul_f32 v[32:33], v[32:33], v[58:59]
	v_pk_mul_f32 v[34:35], v[34:35], v[24:25]
	v_pk_mul_f32 v[28:29], v[28:29], v[60:61]
	v_pk_mul_f32 v[30:31], v[30:31], v[26:27]
	v_cvt_pk_bf16_f32 v20, v48, v49
	v_cvt_pk_bf16_f32 v21, v50, v51
	v_cvt_pk_bf16_f32 v22, v36, v37
	v_cvt_pk_bf16_f32 v23, v38, v39
	v_cvt_pk_bf16_f32 v24, v32, v33
	v_cvt_pk_bf16_f32 v25, v34, v35
	v_cvt_pk_bf16_f32 v26, v28, v29
	v_cvt_pk_bf16_f32 v27, v30, v31
	global_store_dwordx4 v[52:53], v[20:23], off offset:2048
	global_store_dwordx4 v[52:53], v[24:27], off offset:3072
	s_andn2_b64 exec, exec, s[16:17]
	s_cbranch_execz .LBB0_608
; __device__ __forceinline__ unsigned pk2(float lo, float hi) { f32x2_t v = {lo, hi}; bf16x2_t b = __builtin_convertvector(v, bf16x2_t); return __builtin_bit_cast(unsigned, b); }
; __device__ __forceinline__ void rms_half(const bfu* src, const float* gam, bfu* dst, int lane) {
;     float a[8], c[8];
;     ld8f(src + lane * 8, a); ld8f(src + 512 + lane * 8, c);
;     float ss = 0.f;
; #pragma unroll
;     for (int j = 0; j < 8; ++j) ss += a[j] * a[j] + c[j] * c[j];
;     ss = wsum(ss);
;     const float rs = rsqrtf(ss * (1.f / 1024.f) + EPS);
;     float g0[8], g1[8]; ld8f32(gam + lane * 8, g0); ld8f32(gam + 512 + lane * 8, g1);
;     uint4 o0, o1;
;     o0.x = pk2(a[0] * rs * g0[0], a[1] * rs * g0[1]); o0.y = pk2(a[2] * rs * g0[2], a[3] * rs * g0[3]); o0.z = pk2(a[4] * rs * g0[4], a[5] * rs * g0[5]); o0.w = pk2(a[6] * rs * g0[6], a[7] * rs * g0[7]);
;     o1.x = pk2(c[0] * rs * g1[0], c[1] * rs * g1[1]); o1.y = pk2(c[2] * rs * g1[2], c[3] * rs * g1[3]); o1.z = pk2(c[4] * rs * g1[4], c[5] * rs * g1[5]); o1.w = pk2(c[6] * rs * g1[6], c[7] * rs * g1[7]);
;     *(uint4*)(dst + lane * 8) = o0; *(uint4*)(dst + 512 + lane * 8) = o1;
; }
; __device__ __forceinline__ void attn_merge_rms(const Params& p, int row, bfu* dst, int lane) {
;     const bfu* attb = (const bfu*)(p.ws + WS_ATTB); const float* lse = (const float*)(p.ws + WS_LSE);
;     float a[8], c[8];
; #pragma unroll
;     for (int j = 0; j < 8; ++j) { a[j] = 0.f; c[j] = 0.f; }
;     const int h0 = lane >> 3, h1 = 8 + (lane >> 3);
;     float l0[3], l1[3];
; #pragma unroll
;     for (int br = 0; br < 3; ++br) { l0[br] = lse[(size_t)br * (MP * 16) + (size_t)row * 16 + h0]; l1[br] = lse[(size_t)br * (MP * 16) + (size_t)row * 16 + h1]; }
;     const float m0 = fmaxf(fmaxf(l0[0], l0[1]), l0[2]), m1 = fmaxf(fmaxf(l1[0], l1[1]), l1[2]);
;     float w0[3], w1[3];
; #pragma unroll
;     for (int br = 0; br < 3; ++br) { w0[br] = __expf(l0[br] - m0); w1[br] = __expf(l1[br] - m1); }
;     const float i0 = 1.f / (w0[0] + w0[1] + w0[2]), i1 = 1.f / (w1[0] + w1[1] + w1[2]);
; #pragma unroll
;     for (int br = 0; br < 3; ++br) {
;         float x[8], y[8];
;         const bfu* src = attb + (size_t)br * ((size_t)MP * 1024) + (size_t)row * 1024;
;         ld8f(src + lane * 8, x); ld8f(src + 512 + lane * 8, y);
.LBB0_604:
	v_cmp_lt_i32_e32 vcc, s3, v18
	s_and_saveexec_b64 s[8:9], vcc
	s_xor_b64 s[8:9], exec, s[8:9]
	s_cbranch_execz .LBB0_606
	v_mov_b32_e32 v0, v18
	v_lshlrev_b64 v[20:21], 11, v[0:1]
	v_lshl_add_u64 v[30:31], v[6:7], 0, v[20:21]
	global_load_dwordx4 v[22:25], v[30:31], off nt
	global_load_dwordx4 v[26:29], v[30:31], off offset:1024 nt
	s_waitcnt vmcnt(1)
	v_lshlrev_b32_e32 v30, 16, v22
	s_waitcnt vmcnt(0)
	v_lshlrev_b32_e32 v58, 16, v26
	v_and_b32_e32 v59, 0xffff0000, v26
	v_and_b32_e32 v31, 0xffff0000, v22
	v_lshlrev_b32_e32 v26, 16, v27
	v_and_b32_e32 v27, 0xffff0000, v27
	v_pk_mul_f32 v[64:65], v[58:59], v[58:59]
	v_lshlrev_b32_e32 v22, 16, v23
	v_and_b32_e32 v23, 0xffff0000, v23
	v_pk_mul_f32 v[62:63], v[26:27], v[26:27]
	v_pk_fma_f32 v[64:65], v[30:31], v[30:31], v[64:65]
	v_lshlrev_b32_e32 v60, 16, v28
	v_and_b32_e32 v61, 0xffff0000, v28
	v_pk_fma_f32 v[62:63], v[22:23], v[22:23], v[62:63]
	v_add_f32_e32 v47, v64, v65
	v_lshlrev_b32_e32 v56, 16, v24
	v_and_b32_e32 v57, 0xffff0000, v24
	v_pk_mul_f32 v[68:69], v[60:61], v[60:61]
	v_add_f32_e32 v47, v47, v62
	v_lshlrev_b32_e32 v28, 16, v29
	v_and_b32_e32 v29, 0xffff0000, v29
	v_pk_fma_f32 v[68:69], v[56:57], v[56:57], v[68:69]
	v_add_f32_e32 v47, v63, v47
	v_lshlrev_b32_e32 v24, 16, v25
	v_and_b32_e32 v25, 0xffff0000, v25
	v_pk_mul_f32 v[66:67], v[28:29], v[28:29]
	v_add_f32_e32 v47, v68, v47
	v_pk_fma_f32 v[66:67], v[24:25], v[24:25], v[66:67]
	v_add_f32_e32 v47, v69, v47
	v_add_f32_e32 v47, v66, v47
	v_add_f32_e32 v47, v67, v47
	ds_bpermute_b32 v62, v40, v47
	s_waitcnt lgkmcnt(0)
	v_add_f32_e32 v47, v47, v62
	ds_bpermute_b32 v62, v41, v47
	s_waitcnt lgkmcnt(0)
	v_add_f32_e32 v47, v47, v62
	ds_bpermute_b32 v62, v42, v47
	s_waitcnt lgkmcnt(0)
	v_add_f32_e32 v47, v47, v62
	ds_bpermute_b32 v62, v43, v47
	s_waitcnt lgkmcnt(0)
	v_add_f32_e32 v47, v47, v62
	ds_bpermute_b32 v62, v44, v47
	s_waitcnt lgkmcnt(0)
	v_add_f32_e32 v47, v47, v62
	ds_bpermute_b32 v62, v45, v47
	s_waitcnt lgkmcnt(0)
	v_add_f32_e32 v47, v47, v62
	v_fmamk_f32 v47, v47, 0x3a800000, v46
	v_mul_f32_e32 v62, 0x4b800000, v47
	v_cmp_gt_f32_e32 vcc, s20, v47
	s_nop 1
	v_cndmask_b32_e32 v47, v47, v62, vcc
	v_rsq_f32_e32 v47, v47
	s_nop 0
	v_mul_f32_e32 v62, 0x45800000, v47
	v_cndmask_b32_e32 v62, v47, v62, vcc
	v_pk_mul_f32 v[30:31], v[62:63], v[30:31] op_sel_hi:[0,1]
	v_pk_mul_f32 v[64:65], v[62:63], v[22:23] op_sel_hi:[0,1]
	v_pk_mul_f32 v[56:57], v[62:63], v[56:57] op_sel_hi:[0,1]
	v_pk_mul_f32 v[66:67], v[62:63], v[24:25] op_sel_hi:[0,1]
	v_pk_mul_f32 v[58:59], v[62:63], v[58:59] op_sel_hi:[0,1]
	v_pk_mul_f32 v[68:69], v[62:63], v[26:27] op_sel_hi:[0,1]
	v_pk_mul_f32 v[60:61], v[62:63], v[60:61] op_sel_hi:[0,1]
	v_pk_mul_f32 v[62:63], v[62:63], v[28:29] op_sel_hi:[0,1]
	s_waitcnt vmcnt(0)
	v_mov_b64_e32 v[36:37], v[104:105]
	v_mov_b64_e32 v[38:39], v[106:107]
	v_mov_b64_e32 v[32:33], v[108:109]
	v_mov_b64_e32 v[34:35], v[110:111]
	v_mov_b64_e32 v[48:49], v[112:113]
	v_mov_b64_e32 v[50:51], v[114:115]
	v_mov_b64_e32 v[52:53], v[116:117]
	v_mov_b64_e32 v[54:55], v[118:119]
	v_pk_mul_f32 v[22:23], v[52:53], v[30:31]
	v_pk_mul_f32 v[24:25], v[54:55], v[64:65]
	v_pk_mul_f32 v[26:27], v[48:49], v[56:57]
	v_pk_mul_f32 v[28:29], v[50:51], v[66:67]
	v_pk_mul_f32 v[32:33], v[32:33], v[58:59]
	v_pk_mul_f32 v[34:35], v[34:35], v[68:69]
	v_pk_mul_f32 v[36:37], v[36:37], v[60:61]
	v_pk_mul_f32 v[30:31], v[38:39], v[62:63]
	v_mov_b64_e32 v[38:39], v[0:1]
.LBB0_606:
	s_andn2_saveexec_b64 s[18:19], s[8:9]
	s_cbranch_execz .LBB0_603
	v_lshl_add_u64 v[28:29], s[4:5], 0, v[16:17]
	v_add_co_u32_e32 v30, vcc, 0x30f00000, v28
	v_lshl_add_u64 v[36:37], s[4:5], 0, v[14:15]
	s_nop 0
	v_addc_co_u32_e32 v31, vcc, 0, v29, vcc
	v_add_co_u32_e32 v24, vcc, s21, v36
	s_nop 1
	v_addc_co_u32_e32 v25, vcc, 0, v37, vcc
	v_add_co_u32_e32 v32, vcc, 0x31000000, v28
	global_load_dwordx4 v[20:23], v[24:25], off nt
	s_nop 0
	v_addc_co_u32_e32 v33, vcc, 0, v29, vcc
	v_add_co_u32_e32 v28, vcc, 0x31100000, v28
	global_load_dwordx4 v[24:27], v[24:25], off offset:1024 nt
	s_nop 0
	v_addc_co_u32_e32 v29, vcc, 0, v29, vcc
	global_load_dword v0, v[30:31], off nt
	global_load_dword v47, v[30:31], off offset:32 nt
	global_load_dword v60, v[32:33], off nt
	global_load_dword v61, v[32:33], off offset:32 nt
	global_load_dword v62, v[28:29], off nt
	global_load_dword v63, v[28:29], off offset:32 nt
	v_add_co_u32_e32 v38, vcc, s22, v36
	s_waitcnt vmcnt(7)
	v_lshlrev_b32_e32 v54, 16, v22
	v_addc_co_u32_e32 v39, vcc, 0, v37, vcc
	v_add_co_u32_e32 v52, vcc, s23, v36
	global_load_dwordx4 v[28:31], v[38:39], off nt
	global_load_dwordx4 v[32:35], v[38:39], off offset:1024 nt
	v_addc_co_u32_e32 v53, vcc, 0, v37, vcc
	global_load_dwordx4 v[36:39], v[52:53], off nt
	global_load_dwordx4 v[48:51], v[52:53], off offset:1024 nt
	s_waitcnt vmcnt(5)
	v_max3_f32 v64, v0, v60, v62
	s_waitcnt vmcnt(4)
; __device__ __forceinline__ void attn_merge_rms(const Params& p, int row, bfu* dst, int lane) {
;     ...
;     for (int br = 0; br < 3; ++br) { l0[br] = lse[(size_t)br * (MP * 16) + (size_t)row * 16 + h0]; l1[br] = lse[(size_t)br * (MP * 16) + (size_t)row * 16 + h1]; }
;     const float m0 = fmaxf(fmaxf(l0[0], l0[1]), l0[2]), m1 = fmaxf(fmaxf(l1[0], l1[1]), l1[2]);
;     float w0[3], w1[3];
; #pragma unroll
;     for (int br = 0; br < 3; ++br) { w0[br] = __expf(l0[br] - m0); w1[br] = __expf(l1[br] - m1); }
;     const float i0 = 1.f / (w0[0] + w0[1] + w0[2]), i1 = 1.f / (w1[0] + w1[1] + w1[2]);
; #pragma unroll
;     for (int br = 0; br < 3; ++br) {
;         float x[8], y[8];
;         const bfu* src = attb + (size_t)br * ((size_t)MP * 1024) + (size_t)row * 1024;
;         ld8f(src + lane * 8, x); ld8f(src + 512 + lane * 8, y);
;         const float f0 = w0[br] * i0, f1 = w1[br] * i1;
; #pragma unroll
;         for (int j = 0; j < 8; ++j) { a[j] += f0 * x[j]; c[j] += f1 * y[j]; }
	v_max3_f32 v65, v47, v61, v63
	v_sub_f32_e32 v0, v0, v64
	v_sub_f32_e32 v60, v60, v64
	v_sub_f32_e32 v47, v47, v65
	v_sub_f32_e32 v61, v61, v65
	v_sub_f32_e32 v62, v62, v64
	v_mul_f32_e32 v0, 0x3fb8aa3b, v0
	v_mul_f32_e32 v60, 0x3fb8aa3b, v60
	v_sub_f32_e32 v63, v63, v65
	v_mul_f32_e32 v47, 0x3fb8aa3b, v47
	v_mul_f32_e32 v61, 0x3fb8aa3b, v61
	v_mul_f32_e32 v64, 0x3fb8aa3b, v62
	v_exp_f32_e32 v65, v0
	v_exp_f32_e32 v60, v60
	v_mul_f32_e32 v63, 0x3fb8aa3b, v63
	v_exp_f32_e32 v47, v47
	v_exp_f32_e32 v62, v61
	v_exp_f32_e32 v61, v64
	v_exp_f32_e32 v63, v63
	v_add_f32_e32 v0, v65, v60
	v_add_f32_e32 v64, v47, v62
	v_add_f32_e32 v0, v61, v0
	v_add_f32_e32 v64, v63, v64
	v_div_scale_f32 v66, s[8:9], v0, v0, 1.0
	v_div_scale_f32 v68, s[8:9], v64, v64, 1.0
	v_rcp_f32_e32 v69, v66
	v_rcp_f32_e32 v70, v68
	v_div_scale_f32 v67, vcc, 1.0, v0, 1.0
	v_fma_f32 v72, -v66, v69, 1.0
	v_fma_f32 v73, -v68, v70, 1.0
	v_fmac_f32_e32 v69, v72, v69
	v_div_scale_f32 v71, s[8:9], 1.0, v64, 1.0
	v_fmac_f32_e32 v70, v73, v70
	v_mul_f32_e32 v72, v67, v69
	v_mul_f32_e32 v73, v71, v70
	v_fma_f32 v74, -v66, v72, v67
	v_fma_f32 v75, -v68, v73, v71
	v_fmac_f32_e32 v72, v74, v69
	v_fmac_f32_e32 v73, v75, v70
	v_fma_f32 v66, -v66, v72, v67
	v_fma_f32 v67, -v68, v73, v71
	v_div_fmas_f32 v66, v66, v69, v72
	s_mov_b64 vcc, s[8:9]
	v_div_fixup_f32 v0, v66, v0, 1.0
	v_div_fmas_f32 v66, v67, v70, v73
	v_div_fixup_f32 v64, v66, v64, 1.0
	v_mul_f32_e32 v66, v65, v0
	v_pk_mul_f32 v[60:61], v[60:61], v[0:1] op_sel_hi:[1,0]
	v_lshlrev_b32_e32 v56, 16, v24
	v_and_b32_e32 v57, 0xffff0000, v24
	v_lshlrev_b32_e32 v24, 16, v25
	v_and_b32_e32 v25, 0xffff0000, v25
	v_lshlrev_b32_e32 v58, 16, v26
	v_and_b32_e32 v59, 0xffff0000, v26
	v_lshlrev_b32_e32 v26, 16, v27
	v_and_b32_e32 v27, 0xffff0000, v27
	v_mul_f32_e32 v68, v47, v64
	v_and_b32_e32 v55, 0xffff0000, v22
	v_lshlrev_b32_e32 v22, 16, v23
	v_and_b32_e32 v23, 0xffff0000, v23
	v_lshlrev_b32_e32 v52, 16, v20
	v_and_b32_e32 v53, 0xffff0000, v20
	v_lshlrev_b32_e32 v20, 16, v21
	v_and_b32_e32 v21, 0xffff0000, v21
	s_waitcnt vmcnt(3)
	v_lshlrev_b32_e32 v65, 16, v29
	s_waitcnt vmcnt(2)
	v_lshlrev_b32_e32 v70, 16, v35
	v_and_b32_e32 v71, 0xffff0000, v35
	s_waitcnt vmcnt(1)
	v_lshlrev_b32_e32 v35, 16, v36
	v_lshlrev_b32_e32 v83, 16, v37
	v_and_b32_e32 v77, 0xffff0000, v36
	v_and_b32_e32 v37, 0xffff0000, v37
	v_and_b32_e32 v36, 0xffff0000, v29
	v_pk_mul_f32 v[62:63], v[62:63], v[64:65] op_sel_hi:[1,0]
	v_pk_mul_f32 v[94:95], v[60:61], v[36:37]
	s_waitcnt vmcnt(0)
; __device__ __forceinline__ unsigned pk2(float lo, float hi) { f32x2_t v = {lo, hi}; bf16x2_t b = __builtin_convertvector(v, bf16x2_t); return __builtin_bit_cast(unsigned, b); }
; __device__ __forceinline__ float wsum(float v) { v += __shfl_xor(v, 32); v += __shfl_xor(v, 16); v += __shfl_xor(v, 8); v += __shfl_xor(v, 4); v += __shfl_xor(v, 2); v += __shfl_xor(v, 1); return v; }
; __device__ __forceinline__ void attn_merge_rms(const Params& p, int row, bfu* dst, int lane) {
;     ...
;     for (int br = 0; br < 3; ++br) {
;         float x[8], y[8];
;         const bfu* src = attb + (size_t)br * ((size_t)MP * 1024) + (size_t)row * 1024;
;         ld8f(src + lane * 8, x); ld8f(src + 512 + lane * 8, y);
;         const float f0 = w0[br] * i0, f1 = w1[br] * i1;
; #pragma unroll
;         for (int j = 0; j < 8; ++j) { a[j] += f0 * x[j]; c[j] += f1 * y[j]; }
;     }
;     float ss = 0.f;
; #pragma unroll
;     for (int j = 0; j < 8; ++j) ss += a[j] * a[j] + c[j] * c[j];
;     ss = wsum(ss);
;     const float rs = rsqrtf(ss * (1.f / 1024.f) + EPS);
;     const float* gam = p.attn_g;
;     float g0[8], g1[8]; ld8f32(gam + lane * 8, g0); ld8f32(gam + 512 + lane * 8, g1);
;     uint4 o0, o1;
;     o0.x = pk2(a[0] * rs * g0[0], a[1] * rs * g0[1]); o0.y = pk2(a[2] * rs * g0[2], a[3] * rs * g0[3]); o0.z = pk2(a[4] * rs * g0[4], a[5] * rs * g0[5]); o0.w = pk2(a[6] * rs * g0[6], a[7] * rs * g0[7]);
;     o1.x = pk2(c[0] * rs * g1[0], c[1] * rs * g1[1]); o1.y = pk2(c[2] * rs * g1[2], c[3] * rs * g1[3]); o1.z = pk2(c[4] * rs * g1[4], c[5] * rs * g1[5]); o1.w = pk2(c[6] * rs * g1[6], c[7] * rs * g1[7]);
;     *(uint4*)(dst + lane * 8) = o0; *(uint4*)(dst + 512 + lane * 8) = o1;
	v_and_b32_e32 v37, 0xffff0000, v49
	v_and_b32_e32 v36, 0xffff0000, v33
	v_lshlrev_b32_e32 v69, 16, v31
	v_lshlrev_b32_e32 v75, 16, v32
	v_lshlrev_b32_e32 v79, 16, v33
	v_and_b32_e32 v64, 0xffff0000, v32
	v_pk_mul_f32 v[96:97], v[62:63], v[36:37]
	v_and_b32_e32 v33, 0xffff0000, v38
	v_and_b32_e32 v32, 0xffff0000, v30
	v_lshlrev_b32_e32 v88, 16, v48
	v_lshlrev_b32_e32 v89, 16, v49
	v_mul_f32_e32 v78, v60, v65
	v_and_b32_e32 v65, 0xffff0000, v48
	v_mul_f32_e32 v48, v62, v79
	v_pk_mul_f32 v[102:103], v[60:61], v[32:33]
	v_and_b32_e32 v33, 0xffff0000, v50
	v_and_b32_e32 v32, 0xffff0000, v34
	v_pk_fma_f32 v[26:27], v[68:69], v[26:27], 0 op_sel_hi:[0,1,0]
	v_pk_fma_f32 v[24:25], v[68:69], v[24:25], 0 op_sel_hi:[0,1,0]
	v_mov_b32_e32 v49, v96
	v_lshlrev_b32_e32 v81, 16, v34
	v_lshlrev_b32_e32 v87, 16, v39
	v_lshlrev_b32_e32 v91, 16, v50
	v_lshlrev_b32_e32 v72, 16, v51
	v_and_b32_e32 v73, 0xffff0000, v51
	v_pk_mul_f32 v[64:65], v[62:63], v[64:65]
	v_mul_f32_e32 v92, v63, v89
	v_pk_mul_f32 v[50:51], v[62:63], v[32:33]
	v_pk_fma_f32 v[26:27], v[62:63], v[70:71], v[26:27] op_sel_hi:[0,1,1]
	v_pk_add_f32 v[24:25], v[24:25], v[48:49]
	v_mov_b32_e32 v93, v97
	v_lshlrev_b32_e32 v47, 16, v28
	v_lshlrev_b32_e32 v67, 16, v30
	v_and_b32_e32 v76, 0xffff0000, v28
	v_mul_f32_e32 v28, v62, v75
	v_mul_f32_e32 v86, v62, v81
	v_mul_f32_e32 v88, v63, v88
	v_mul_f32_e32 v100, v63, v91
	v_mul_f32_e32 v30, v61, v87
	v_pk_fma_f32 v[62:63], v[62:63], v[72:73], v[26:27] op_sel:[1,0,0]
	v_pk_fma_f32 v[26:27], v[68:69], v[58:59], 0 op_sel_hi:[0,1,0]
	v_mov_b32_e32 v87, v50
	v_pk_add_f32 v[48:49], v[24:25], v[92:93]
	v_pk_fma_f32 v[24:25], v[68:69], v[56:57], 0 op_sel_hi:[0,1,0]
	v_mov_b32_e32 v29, v64
	v_lshlrev_b32_e32 v85, 16, v38
	v_and_b32_e32 v33, 0xffff0000, v39
	v_and_b32_e32 v32, 0xffff0000, v31
	v_pk_add_f32 v[26:27], v[26:27], v[86:87]
	v_mov_b32_e32 v101, v51
	v_pk_add_f32 v[24:25], v[24:25], v[28:29]
	v_mov_b32_e32 v89, v65
	v_mul_f32_e32 v74, v60, v47
	v_pk_mul_f32 v[76:77], v[60:61], v[76:77]
	v_mul_f32_e32 v80, v60, v67
	v_mul_f32_e32 v82, v60, v69
	v_mul_f32_e32 v84, v61, v35
	v_mul_f32_e32 v90, v61, v83
	v_mul_f32_e32 v98, v61, v85
	v_pk_mul_f32 v[60:61], v[60:61], v[32:33]
	v_pk_add_f32 v[50:51], v[26:27], v[100:101]
	v_pk_add_f32 v[56:57], v[24:25], v[88:89]
	v_pk_fma_f32 v[68:69], v[66:67], v[22:23], 0 op_sel_hi:[0,1,0]
	v_pk_fma_f32 v[52:53], v[66:67], v[52:53], 0 op_sel_hi:[0,1,0]
	v_mov_b32_e32 v75, v76
	v_pk_fma_f32 v[20:21], v[66:67], v[20:21], 0 op_sel_hi:[0,1,0]
	v_mov_b32_e32 v79, v94
	v_pk_add_f32 v[52:53], v[52:53], v[74:75]
	v_mov_b32_e32 v85, v77
	v_pk_mul_f32 v[64:65], v[56:57], v[56:57]
	v_pk_add_f32 v[20:21], v[20:21], v[78:79]
	v_mov_b32_e32 v91, v95
	v_pk_add_f32 v[52:53], v[52:53], v[84:85]
	v_pk_mul_f32 v[58:59], v[48:49], v[48:49]
	v_mov_b32_e32 v83, v60
	v_pk_fma_f32 v[54:55], v[66:67], v[54:55], 0 op_sel_hi:[0,1,0]
	v_mov_b32_e32 v81, v102
	v_pk_add_f32 v[20:21], v[20:21], v[90:91]
	v_pk_fma_f32 v[64:65], v[52:53], v[52:53], v[64:65]
	v_pk_add_f32 v[68:69], v[68:69], v[82:83]
	v_mov_b32_e32 v31, v61
	v_pk_add_f32 v[54:55], v[54:55], v[80:81]
	v_mov_b32_e32 v99, v103
	v_pk_fma_f32 v[58:59], v[20:21], v[20:21], v[58:59]
	v_add_f32_e32 v0, v64, v65
	v_pk_add_f32 v[30:31], v[68:69], v[30:31]
	v_pk_add_f32 v[54:55], v[54:55], v[98:99]
	v_pk_mul_f32 v[68:69], v[50:51], v[50:51]
	v_add_f32_e32 v0, v0, v58
	v_pk_fma_f32 v[68:69], v[54:55], v[54:55], v[68:69]
	v_add_f32_e32 v0, v59, v0
	v_pk_mul_f32 v[60:61], v[62:63], v[62:63]
	v_add_f32_e32 v0, v68, v0
	v_pk_fma_f32 v[60:61], v[30:31], v[30:31], v[60:61]
	v_add_f32_e32 v0, v69, v0
	v_add_f32_e32 v0, v60, v0
	v_add_f32_e32 v0, v61, v0
	ds_bpermute_b32 v47, v40, v0
	s_waitcnt lgkmcnt(0)
	v_add_f32_e32 v0, v0, v47
	ds_bpermute_b32 v47, v41, v0
	s_waitcnt lgkmcnt(0)
	v_add_f32_e32 v0, v0, v47
	ds_bpermute_b32 v47, v42, v0
	s_waitcnt lgkmcnt(0)
	v_add_f32_e32 v0, v0, v47
	ds_bpermute_b32 v47, v43, v0
	s_waitcnt lgkmcnt(0)
	v_add_f32_e32 v0, v0, v47
	ds_bpermute_b32 v47, v44, v0
	s_waitcnt lgkmcnt(0)
	v_add_f32_e32 v0, v0, v47
	ds_bpermute_b32 v47, v45, v0
	s_waitcnt lgkmcnt(0)
	v_add_f32_e32 v0, v0, v47
	v_fmamk_f32 v0, v0, 0x3a800000, v46
	v_mul_f32_e32 v47, 0x4b800000, v0
	v_cmp_gt_f32_e32 vcc, s20, v0
	s_nop 1
	v_cndmask_b32_e32 v0, v0, v47, vcc
	v_rsq_f32_e32 v0, v0
	s_nop 0
	v_mul_f32_e32 v47, 0x45800000, v0
	v_cndmask_b32_e32 v0, v0, v47, vcc
	v_pk_mul_f32 v[20:21], v[20:21], v[0:1] op_sel_hi:[1,0]
	v_pk_mul_f32 v[52:53], v[52:53], v[0:1] op_sel_hi:[1,0]
	s_waitcnt vmcnt(0)
	v_mov_b64_e32 v[36:37], v[104:105]
	v_mov_b64_e32 v[38:39], v[106:107]
	v_mov_b64_e32 v[32:33], v[108:109]
	v_mov_b64_e32 v[34:35], v[110:111]
	v_mov_b64_e32 v[26:27], v[112:113]
	v_mov_b64_e32 v[28:29], v[114:115]
	v_mov_b64_e32 v[22:23], v[116:117]
	v_mov_b64_e32 v[24:25], v[118:119]
	v_pk_mul_f32 v[24:25], v[24:25], v[20:21]
	v_pk_mul_f32 v[20:21], v[54:55], v[0:1] op_sel_hi:[1,0]
	v_pk_mul_f32 v[22:23], v[22:23], v[52:53]
	v_pk_mul_f32 v[26:27], v[26:27], v[20:21]
	v_pk_mul_f32 v[20:21], v[30:31], v[0:1] op_sel_hi:[1,0]
	s_nop 0
	v_pk_mul_f32 v[28:29], v[28:29], v[20:21]
	v_pk_mul_f32 v[20:21], v[56:57], v[0:1] op_sel_hi:[1,0]
	s_nop 0
	v_pk_mul_f32 v[32:33], v[32:33], v[20:21]
	v_pk_mul_f32 v[20:21], v[48:49], v[0:1] op_sel_hi:[1,0]
	s_nop 0
	v_pk_mul_f32 v[34:35], v[34:35], v[20:21]
	v_pk_mul_f32 v[20:21], v[50:51], v[0:1] op_sel_hi:[1,0]
	s_nop 0
	v_pk_mul_f32 v[36:37], v[36:37], v[20:21]
	v_pk_mul_f32 v[20:21], v[62:63], v[0:1] op_sel_hi:[1,0]
	s_nop 0
	v_pk_mul_f32 v[30:31], v[38:39], v[20:21]
	v_mov_b64_e32 v[38:39], v[18:19]
	v_mov_b64_e32 v[20:21], v[12:13]
	s_branch .LBB0_603
